# P7 visits its two tiles in swapped order (most recently written ACT row band first)
# speedup vs baseline: 1.0181x; 1.0021x over previous
;     __host__ __device__ bool next(int i, Unit& u) const {
;         const long L = (long)i * G + c; if (L >= nwg) return false;
;         int wgid = (int)L; { const int q = nwg / NXCD, r = nwg % NXCD, xcd = wgid % NXCD, off = wgid / NXCD; wgid = (xcd < r ? xcd * (q + 1) : r * (q + 1) + (xcd - r) * q) + off; }
;         const int nig = WGM * nN, gid = wgid / nig, fm = gid * WGM, gsz = (nM - fm) < WGM ? (nM - fm) : WGM;
;         u.pm = fm + ((wgid % nig) % gsz); u.pn = (wgid % nig) / gsz; return true;
.LBB0_790:
	s_lshl_b32 s24, s68, 6
	s_and_b64 s[14:15], s[94:95], exec
	s_cselect_b32 s14, s60, s24
	s_add_i32 s14, s14, s67
	s_cmp_eq_u32 s20, 0x100
	s_cselect_b32 s15, 32, 0
	s_add_i32 s14, s14, s15
	s_ashr_i32 s15, s14, 31
	s_lshr_b32 s15, s15, 27
	s_add_i32 s15, s14, s15
	s_ashr_i32 s24, s15, 5
	s_and_b32 s15, s15, 0xffe0
	s_sub_i32 s14, s14, s15
	s_bfe_i32 s15, s14, 0x80000
	s_bfe_u32 s15, s15, 0x3000c
	s_add_i32 s15, s14, s15
	s_bfe_i32 s25, s15, 0x80000
	s_and_b32 s15, s15, 0xf8
	s_sub_i32 s14, s14, s15
	s_lshl_b32 s24, s24, 3
	s_sext_i32_i16 s25, s25
	s_sext_i32_i8 s14, s14
	s_add_i32 s58, s24, s14
	s_ashr_i32 s55, s25, 3
	s_and_b64 vcc, exec, s[10:11]
	s_cbranch_vccnz .LBB0_780

;     __host__ __device__ bool next(int i, Unit& u) const {
;         const long L = (long)i * G + c; if (L >= nwg) return false;
;         int wgid = (int)L; { const int q = nwg / NXCD, r = nwg % NXCD, xcd = wgid % NXCD, off = wgid / NXCD; wgid = (xcd < r ? xcd * (q + 1) : r * (q + 1) + (xcd - r) * q) + off; }
;         const int nig = WGM * nN, gid = wgid / nig, fm = gid * WGM, gsz = (nM - fm) < WGM ? (nM - fm) : WGM;
;         u.pm = fm + ((wgid % nig) % gsz); u.pn = (wgid % nig) / gsz; return true;
.LBB0_796:
	s_add_i32 s62, s62, 1
	s_mul_i32 s12, s62, s21
	s_mul_hi_u32 s13, s62, s20
	s_add_i32 s13, s13, s12
	s_mul_i32 s12, s62, s20
	s_add_u32 s12, s12, s2
	s_addc_u32 s13, s13, s3
	v_cmp_gt_i64_e32 vcc, s[12:13], v[166:167]
	v_cmp_lt_i64_e64 s[14:15], s[12:13], v[164:165]
	s_cbranch_vccnz .LBB0_802
	s_cmp_eq_u32 s20, 0x100
	s_cselect_b32 s24, 0x100, 0
	s_xor_b32 s12, s12, s24
	s_ashr_i32 s13, s12, 31
	s_lshr_b32 s13, s13, 29
	s_add_i32 s24, s12, s13
	s_and_b32 s13, s24, -8
	s_sub_i32 s34, s12, s13
	s_cmp_gt_i32 s34, -1
	s_mov_b64 s[12:13], -1
	s_cbranch_scc0 .LBB0_799
	s_lshl_b32 s35, s34, 6
	s_mov_b64 s[12:13], 0
